# long-conv filter staging as straight-line masked stores (prompt path)
# speedup vs baseline: 1.0031x; 1.0031x over previous
; __device__ __forceinline__ void toeplitz_item(const Params& p, int layer, int half, int c, bf16* sm, int dry, unsigned* done_ctr) {
;     ...
;     __syncthreads();
; #pragma unroll
;     for (int i = 0; i < 3; ++i) {
;       const int x = tid + 256 * i;
;       if (x < 648) {
; #pragma unroll
;         for (int qq = 0; qq < 8; ++qq) {
;           const int y = x - qq;
;           if (y >= 0 && (y >> 3) < 80) sW[(qq * 83 + (y >> 3)) * 8 + (y & 7)] = wreg[i];
;         }
;       }
;     }
;     __syncthreads();
;     if (bt + 1 < nbatch) {
;       const int m0 = OFF - 128 * (D0 + 4 + 3) - 128;
; #pragma unroll
;       for (int i = 0; i < 3; ++i) { int x = tid + 256 * i; wreg[i] = x < 648 ? rho[m0 + x] : (bf16)0; }
.LBB0_1148:
	s_waitcnt lgkmcnt(0)
	s_barrier
	s_mov_b64 s[2:3], exec
	s_waitcnt vmcnt(0)
	s_and_b64 exec, s[46:47], vcc
	ds_write_b16 v120, v121 offset:35088
	s_and_b64 exec, s[46:47], s[90:91]
	ds_write_b16 v119, v121 offset:35088
	s_and_b64 exec, s[46:47], s[88:89]
	ds_write_b16 v118, v121 offset:35088
	s_and_b64 exec, s[46:47], s[86:87]
	ds_write_b16 v117, v121 offset:35088
	s_and_b64 exec, s[46:47], s[84:85]
	ds_write_b16 v116, v121 offset:35088
	s_and_b64 exec, s[46:47], s[82:83]
	ds_write_b16 v115, v121 offset:35088
	s_and_b64 exec, s[46:47], s[80:81]
	ds_write_b16 v114, v121 offset:35088
	s_and_b64 exec, s[46:47], s[78:79]
	ds_write_b16 v113, v121 offset:35088
	s_and_b64 exec, s[44:45], s[20:21]
	ds_write_b16 v112, v96 offset:35088
	s_and_b64 exec, s[44:45], s[38:39]
	ds_write_b16 v111, v96 offset:35088
	s_and_b64 exec, s[44:45], s[36:37]
	ds_write_b16 v110, v96 offset:35088
	s_and_b64 exec, s[44:45], s[34:35]
	ds_write_b16 v109, v96 offset:35088
	s_and_b64 exec, s[44:45], s[30:31]
	ds_write_b16 v108, v96 offset:35088
	s_and_b64 exec, s[44:45], s[28:29]
	ds_write_b16 v107, v96 offset:35088
	s_and_b64 exec, s[44:45], s[26:27]
	ds_write_b16 v106, v96 offset:35088
	s_and_b64 exec, s[44:45], s[24:25]
	ds_write_b16 v105, v96 offset:35088
	s_and_b64 exec, s[42:43], s[22:23]
	ds_write_b16 v104, v95 offset:35088
	s_and_b64 exec, s[42:43], s[58:59]
	ds_write_b16 v103, v95 offset:35088
	s_and_b64 exec, s[42:43], s[56:57]
	ds_write_b16 v102, v95 offset:35088
	s_and_b64 exec, s[42:43], s[96:97]
	ds_write_b16 v101, v95 offset:35088
	s_and_b64 exec, s[42:43], s[94:95]
	ds_write_b16 v100, v95 offset:35088
	s_and_b64 exec, s[42:43], s[70:71]
	ds_write_b16 v99, v95 offset:35088
	s_and_b64 exec, s[42:43], s[66:67]
	ds_write_b16 v98, v95 offset:35088
	s_and_b64 exec, s[42:43], s[64:65]
	ds_write_b16 v97, v95 offset:35088
	s_mov_b64 exec, s[2:3]
	s_waitcnt vmcnt(0)
	v_mov_b32_e32 v96, 0
	v_mov_b32_e32 v121, 0
	s_waitcnt lgkmcnt(0)
	s_barrier
	s_and_saveexec_b64 s[2:3], s[46:47]
	s_cbranch_execz .LBB0_1202
	global_load_ushort v121, v[86:87], off
	s_or_b64 exec, exec, s[2:3]
	s_and_saveexec_b64 s[2:3], s[44:45]
	s_cbranch_execnz .LBB0_1203
